# gating phase: layer-norm wait counts only the loads issued a unit ahead (vmcnt 4 instead of 0), first-unit wait moved to the loop entry
# speedup vs baseline: 1.0536x; 1.0040x over previous
; #define tid (otid())
; #define wave (__builtin_amdgcn_readfirstlane((int)(threadIdx.x >> 6)))
; __global__ void __launch_bounds__(512, 2) mega_fwd(Args a) {
;     ...
;         const int r32 = lane & 31, hi = lane >> 5, iblk = wave >> 1, dblk = wave & 1;
;         const int jt = tid >> 2, qd = tid & 3;
;         u32x4 r0, r1; f32x4 lgv[4], lbv[4];
;         const int ustep = (G == 256) ? 1 : G;
;         const int jx = vcu & 31;
;         const int u0 = (G == 256) ? (256 * (vcu >> 5) + (jx < 16 ? 7 * jx : 112 + 9 * (jx - 16))) : vcu;
;         const int ucnt = (G == 256) ? (bx < 128 ? 7 : 9) : (vcu < 2048 ? (2047 - vcu) / G + 1 : 0);
;         if (ucnt > 0) { const bf16_t* vp = Z + ((size_t)(u0 >> 3) * 128 + jt) * NZ + 1024 + (u0 & 7) * 64 + 16 * qd; r0 = *(const u32x4*)vp; r1 = *(const u32x4*)(vp + 8);
; #pragma unroll
;             for (int e4 = 0; e4 < 4; ++e4) { lgv[e4] = *(const f32x4*)(KA->gm_ln_g + (u0 & 7) * 64 + 16 * qd + 4 * e4); lbv[e4] = *(const f32x4*)(KA->gm_ln_b + (u0 & 7) * 64 + 16 * qd + 4 * e4); } }
.LBB0_340:
	s_cmp_lt_i32 s18, 1
	s_cbranch_scc1 .LBB0_361
	s_load_dwordx2 s[8:9], s[6:7], 0xb8
	s_load_dwordx4 s[40:43], s[6:7], 0x58
	s_and_b64 s[4:5], s[4:5], exec
	s_cselect_b32 s19, 1, s28
	s_ashr_i32 s4, s39, 3
	v_ashrrev_i32_e32 v84, 2, v2
	s_ashr_i32 s5, s4, 31
	s_lshl_b64 s[4:5], s[4:5], 7
	v_ashrrev_i32_e32 v85, 31, v84
	v_and_b32_e32 v6, 3, v3
	v_lshl_add_u64 v[2:3], s[4:5], 0, v[84:85]
	s_movk_i32 s33, 0xc00
	s_waitcnt lgkmcnt(0)
	v_mov_b64_e32 v[4:5], s[8:9]
	v_mad_u64_u32 v[4:5], s[4:5], v2, s33, v[4:5]
	s_lshl_b32 s4, s39, 6
	s_and_b32 s4, s4, 0x1c0
	v_mad_i32_i24 v5, v3, s33, v5
	s_lshl_b32 s10, s4, 1
	s_mov_b32 s11, 0
	v_lshl_add_u64 v[2:3], v[4:5], 0, s[10:11]
	v_mov_b32_e32 v87, 0
	v_lshlrev_b32_e32 v86, 5, v6
	v_lshl_add_u64 v[2:3], v[2:3], 0, v[86:87]
	s_mov_b64 s[12:13], 0x6000800
	s_mov_b32 s36, 0x6000000
	s_lshl_b32 s10, s4, 2
	v_lshl_add_u64 v[4:5], v[2:3], 0, s[12:13]
	v_add_co_u32_e32 v2, vcc, s36, v2
	s_add_u32 s4, s40, s10
	s_nop 0
	v_addc_co_u32_e32 v3, vcc, 0, v3, vcc
	s_addc_u32 s5, s41, 0
	global_load_dwordx4 v[16:19], v[2:3], off offset:2048
	global_load_dwordx4 v[20:23], v[4:5], off offset:16
	v_lshlrev_b32_e32 v2, 6, v6
	s_add_u32 s22, s42, s10
	s_load_dwordx2 s[16:17], s[6:7], 0x70
	s_addc_u32 s23, s43, 0
	global_load_dwordx4 v[24:27], v2, s[4:5] offset:48
	global_load_dwordx4 v[28:31], v2, s[4:5] offset:32
	global_load_dwordx4 v[32:35], v2, s[4:5] offset:16
	global_load_dwordx4 v[36:39], v2, s[4:5]
	global_load_dwordx4 v[56:59], v2, s[22:23] offset:48
	global_load_dwordx4 v[60:63], v2, s[22:23] offset:32
	global_load_dwordx4 v[64:67], v2, s[22:23] offset:16
	global_load_dwordx4 v[68:71], v2, s[22:23]
	v_and_b32_e32 v4, 31, v0
	v_mbcnt_hi_u32_b32 v0, -1, v254
	v_and_b32_e32 v3, 64, v0
	v_xor_b32_e32 v2, 1, v0
	v_add_u32_e32 v3, 64, v3
	v_cmp_lt_i32_e32 vcc, v2, v3
	s_lshr_b32 s4, s20, 2
	s_and_b32 s4, s4, 0x3fffffe0
	v_cndmask_b32_e32 v2, v0, v2, vcc
	v_lshlrev_b32_e32 v89, 2, v2
	v_xor_b32_e32 v2, 2, v0
	v_cmp_lt_i32_e32 vcc, v2, v3
	v_or_b32_e32 v90, s4, v4
	s_lshr_b32 s4, s20, 1
	v_bfe_u32 v1, v1, 5, 1
	v_cndmask_b32_e32 v0, v0, v2, vcc
	s_and_b32 s10, s4, 32
	v_lshlrev_b32_e32 v97, 2, v0
	v_lshlrev_b32_e32 v0, 2, v1
	v_lshlrev_b32_e32 v86, 4, v1
	v_or_b32_e32 v1, s10, v4
	v_lshl_add_u64 v[2:3], s[8:9], 0, v[86:87]
	s_mov_b64 s[4:5], 0x180000
	s_cmpk_gt_u32 s20, 0xff
	v_mul_u32_u24_e32 v1, 0x110, v1
	v_lshl_add_u32 v5, v84, 1, 0
	v_lshl_add_u64 v[92:93], v[2:3], 0, s[4:5]
	s_cselect_b64 s[20:21], -1, 0
	v_add3_u32 v108, 0, v1, v86
	v_mul_u32_u24_e32 v1, 0x1100, v6
	s_add_i32 s4, s19, s39
	v_lshlrev_b32_e32 v88, 4, v6
	v_mov_b32_e32 v91, v87
	s_lshl_b32 s37, s4, 6
	s_lshl_b32 s42, s19, 6
	v_mov_b32_e32 v109, 0x358637bd
	s_mov_b32 s43, 0x800000
	v_add_u32_e32 v110, v5, v1
	v_lshlrev_b32_e32 v86, 1, v0
	s_mov_b64 s[22:23], 0x6000400
	s_lshl_b32 s38, s10, 1
	s_mov_b64 s[40:41], 0x14a00400
	s_mov_b32 s44, 0x14a00000
	s_mov_b32 s45, 0
	s_waitcnt vmcnt(0)
	s_branch .LBB0_343

; __device__ __forceinline__ unsigned pk2(float lo, float hi) { f32x2_t v = {lo, hi}; bf16x2_t b = __builtin_convertvector(v, bf16x2_t); return __builtin_bit_cast(unsigned, b); }
; __device__ __forceinline__ float bf_lo(unsigned u) { return __uint_as_float(u << 16); }
; __device__ __forceinline__ float bf_hi(unsigned u) { return __uint_as_float(u & 0xffff0000u); }
; __global__ void __launch_bounds__(512, 2) mega_fwd(Args a) {
;     ...
;             {
;                 float xv[16];
;                 xv[0] = bf_lo(r0.x); xv[1] = bf_hi(r0.x); xv[2] = bf_lo(r0.y); xv[3] = bf_hi(r0.y); xv[4] = bf_lo(r0.z); xv[5] = bf_hi(r0.z); xv[6] = bf_lo(r0.w); xv[7] = bf_hi(r0.w);
;                 xv[8] = bf_lo(r1.x); xv[9] = bf_hi(r1.x); xv[10] = bf_lo(r1.y); xv[11] = bf_hi(r1.y); xv[12] = bf_lo(r1.z); xv[13] = bf_hi(r1.z); xv[14] = bf_lo(r1.w); xv[15] = bf_hi(r1.w);
;                 float sm = 0.f;
; #pragma unroll
;                 for (int e = 0; e < 16; ++e) sm += xv[e];
;                 sm += __shfl_xor(sm, 1); sm += __shfl_xor(sm, 2);
;                 const float mu = sm * (1.0f / 64.0f); float q = 0.f;
; #pragma unroll
;                 for (int e = 0; e < 16; ++e) { xv[e] -= mu; q += xv[e] * xv[e]; }
;                 q += __shfl_xor(q, 1); q += __shfl_xor(q, 2);
;                 const float rstd = rsqrtf(q * (1.0f / 64.0f) + EPS);
; #pragma unroll
;                 for (int e = 0; e < 16; ++e) { const float y = xv[e] * rstd * lgv[e >> 2][e & 3] + lbv[e >> 2][e & 3]; VLT[(16 * qd + e) * VLP + jt] = (bf16_t)(pk2(y, 0.f) & 0xffffu); }
;             }
;             const int un = u + ustep;
;             if (ui + 1 < ucnt) { const bf16_t* vp = Z + ((size_t)(un >> 3) * 128 + jt) * NZ + 1024 + (un & 7) * 64 + 16 * qd; r0 = *(const u32x4*)vp; r1 = *(const u32x4*)(vp + 8);
; #pragma unroll
;                 for (int e4 = 0; e4 < 4; ++e4) { lgv[e4] = *(const f32x4*)(KA->gm_ln_g + (un & 7) * 64 + 16 * qd + 4 * e4); lbv[e4] = *(const f32x4*)(KA->gm_ln_b + (un & 7) * 64 + 16 * qd + 4 * e4); } }
.LBB0_343:
	s_waitcnt vmcnt(9)
	v_lshlrev_b32_e32 v12, 16, v16
	v_and_b32_e32 v13, 0xffff0000, v16
	v_add_f32_e32 v0, 0, v12
	v_lshlrev_b32_e32 v14, 16, v17
	v_add_f32_e32 v0, v0, v13
	v_and_b32_e32 v15, 0xffff0000, v17
	v_add_f32_e32 v0, v0, v14
	v_lshlrev_b32_e32 v72, 16, v18
	v_add_f32_e32 v0, v0, v15
	v_and_b32_e32 v73, 0xffff0000, v18
	v_add_f32_e32 v0, v0, v72
	v_lshlrev_b32_e32 v74, 16, v19
	v_add_f32_e32 v0, v0, v73
	v_and_b32_e32 v75, 0xffff0000, v19
	v_add_f32_e32 v0, v0, v74
	v_add_f32_e32 v8, v0, v75
	s_waitcnt vmcnt(8)
	v_lshlrev_b32_e32 v6, 16, v20
	v_and_b32_e32 v7, 0xffff0000, v20
	v_add_f32_e32 v8, v8, v6
	v_lshlrev_b32_e32 v4, 16, v21
	v_add_f32_e32 v8, v8, v7
	v_and_b32_e32 v5, 0xffff0000, v21
	v_add_f32_e32 v8, v8, v4
	v_lshlrev_b32_e32 v2, 16, v22
	v_add_f32_e32 v8, v8, v5
	v_and_b32_e32 v3, 0xffff0000, v22
	v_add_f32_e32 v8, v8, v2
	v_lshlrev_b32_e32 v0, 16, v23
	v_add_f32_e32 v8, v8, v3
	v_and_b32_e32 v1, 0xffff0000, v23
	v_add_f32_e32 v8, v8, v0
	v_add_f32_e32 v8, v8, v1
	ds_bpermute_b32 v9, v89, v8
	s_add_i32 s46, s39, s19
	s_add_i32 s45, s45, 1
	s_cmp_ge_i32 s45, s18
	s_waitcnt lgkmcnt(0)
	v_add_f32_e32 v8, v8, v9
	ds_bpermute_b32 v9, v97, v8
	s_waitcnt lgkmcnt(0)
	v_add_f32_e32 v9, v8, v9
	v_fmac_f32_e32 v13, 0xbc800000, v9
	v_fmac_f32_e32 v12, 0xbc800000, v9
	v_mul_f32_e32 v76, v13, v13
	v_fmac_f32_e32 v76, v12, v12
	v_fmac_f32_e32 v14, 0xbc800000, v9
	v_fmac_f32_e32 v76, v14, v14
	v_fmac_f32_e32 v15, 0xbc800000, v9
	v_fmac_f32_e32 v76, v15, v15
	v_fmac_f32_e32 v72, 0xbc800000, v9
	v_fmac_f32_e32 v76, v72, v72
	v_fmac_f32_e32 v73, 0xbc800000, v9
	v_mul_f32_e32 v8, 0x3c800000, v9
	v_fmac_f32_e32 v76, v73, v73
	v_fmac_f32_e32 v74, 0xbc800000, v9
	v_fmac_f32_e32 v76, v74, v74
	v_fmac_f32_e32 v75, 0xbc800000, v9
	v_pk_add_f32 v[6:7], v[6:7], v[8:9] op_sel_hi:[1,0] neg_lo:[0,1] neg_hi:[0,1]
	v_fmac_f32_e32 v76, v75, v75
	v_pk_mul_f32 v[10:11], v[6:7], v[6:7]
	s_nop 0
	v_add_f32_e32 v9, v76, v10
	v_add_f32_e32 v9, v9, v11
	v_pk_add_f32 v[4:5], v[4:5], v[8:9] op_sel_hi:[1,0] neg_lo:[0,1] neg_hi:[0,1]
	s_nop 0
	v_pk_mul_f32 v[10:11], v[4:5], v[4:5]
	s_nop 0
	v_add_f32_e32 v9, v9, v10
	v_add_f32_e32 v9, v9, v11
	v_pk_add_f32 v[2:3], v[2:3], v[8:9] op_sel_hi:[1,0] neg_lo:[0,1] neg_hi:[0,1]
	s_nop 0
	v_pk_mul_f32 v[10:11], v[2:3], v[2:3]
	s_nop 0
	v_add_f32_e32 v9, v9, v10
	v_pk_add_f32 v[0:1], v[0:1], v[8:9] op_sel_hi:[1,0] neg_lo:[0,1] neg_hi:[0,1]
	v_add_f32_e32 v10, v9, v11
	v_pk_mul_f32 v[8:9], v[0:1], v[0:1]
	s_nop 0
	v_add_f32_e32 v8, v10, v8
	v_add_f32_e32 v8, v8, v9
	ds_bpermute_b32 v9, v89, v8
	s_waitcnt lgkmcnt(0)
	v_add_f32_e32 v8, v8, v9
	ds_bpermute_b32 v9, v97, v8
	s_waitcnt lgkmcnt(0)
	v_add_f32_e32 v8, v8, v9
	v_fmamk_f32 v8, v8, 0x3c800000, v109
	v_mul_f32_e32 v9, 0x4b800000, v8
	v_cmp_gt_f32_e32 vcc, s43, v8
	s_nop 1
	v_cndmask_b32_e32 v8, v8, v9, vcc
	v_rsq_f32_e32 v8, v8
	s_nop 0
	v_mul_f32_e32 v9, 0x45800000, v8
	v_cndmask_b32_e32 v8, v8, v9, vcc
	v_mul_f32_e32 v9, v8, v12
	s_waitcnt vmcnt(4)
	v_fma_f32 v9, v9, v36, v68
	v_cvt_pk_bf16_f32 v9, v9, s0
	ds_write_b16 v110, v9
	v_mul_f32_e32 v9, v8, v13
	v_fma_f32 v9, v9, v37, v69
	v_cvt_pk_bf16_f32 v9, v9, s0
	ds_write_b16 v110, v9 offset:272
	v_mul_f32_e32 v9, v8, v14
	v_fma_f32 v9, v9, v38, v70
	v_cvt_pk_bf16_f32 v9, v9, s0
	ds_write_b16 v110, v9 offset:544
	v_mul_f32_e32 v9, v8, v15
	v_fma_f32 v9, v9, v39, v71
	v_cvt_pk_bf16_f32 v9, v9, s0
	ds_write_b16 v110, v9 offset:816
	v_mul_f32_e32 v9, v8, v72
	v_fma_f32 v9, v9, v32, v64
	v_cvt_pk_bf16_f32 v9, v9, s0
	ds_write_b16 v110, v9 offset:1088
	v_mul_f32_e32 v9, v8, v73
	v_fma_f32 v9, v9, v33, v65
	v_cvt_pk_bf16_f32 v9, v9, s0
	ds_write_b16 v110, v9 offset:1360
	v_mul_f32_e32 v9, v8, v74
	v_mul_f32_e32 v6, v8, v6
	v_mul_f32_e32 v4, v8, v4
	v_mul_f32_e32 v2, v8, v2
	v_mul_f32_e32 v0, v8, v0
	v_fma_f32 v9, v9, v34, v66
	v_fma_f32 v6, v6, v28, v60
	v_fma_f32 v4, v4, v30, v62
	v_fma_f32 v2, v2, v24, v56
	v_fma_f32 v0, v0, v26, v58
	v_cvt_pk_bf16_f32 v9, v9, s0
	v_cvt_pk_bf16_f32 v6, v6, s0
	v_cvt_pk_bf16_f32 v4, v4, s0
	v_cvt_pk_bf16_f32 v2, v2, s0
	v_cvt_pk_bf16_f32 v0, v0, s0
	ds_write_b16 v110, v9 offset:1632
	v_mul_f32_e32 v9, v8, v75
	ds_write_b16 v110, v6 offset:2176
	v_mul_f32_e32 v6, v8, v7
	ds_write_b16 v110, v4 offset:2720
	v_mul_f32_e32 v4, v8, v5
	ds_write_b16 v110, v2 offset:3264
	v_mul_f32_e32 v2, v8, v3
	ds_write_b16 v110, v0 offset:3808
	v_mul_f32_e32 v0, v8, v1
	v_fma_f32 v9, v9, v35, v67
	v_fma_f32 v6, v6, v29, v61
	v_fma_f32 v4, v4, v31, v63
	v_fma_f32 v2, v2, v25, v57
	v_fma_f32 v0, v0, v27, v59
	v_cvt_pk_bf16_f32 v9, v9, s0
	v_cvt_pk_bf16_f32 v6, v6, s0
	v_cvt_pk_bf16_f32 v4, v4, s0
	v_cvt_pk_bf16_f32 v2, v2, s0
	v_cvt_pk_bf16_f32 v0, v0, s0
	ds_write_b16 v110, v9 offset:1904
	ds_write_b16 v110, v6 offset:2448
	ds_write_b16 v110, v4 offset:2992
	ds_write_b16 v110, v2 offset:3536
	ds_write_b16 v110, v0 offset:4080
	s_cbranch_scc1 .LBB0_345
	s_load_dwordx2 s[4:5], s[6:7], 0xb8
	s_ashr_i32 s48, s46, 3
	s_ashr_i32 s49, s48, 31
	s_lshl_b64 s[48:49], s[48:49], 7
	v_lshl_add_u64 v[0:1], s[48:49], 0, v[84:85]
	s_load_dwordx4 s[48:51], s[6:7], 0x58
	s_waitcnt lgkmcnt(0)
	v_mov_b64_e32 v[2:3], s[4:5]
	v_mad_u64_u32 v[2:3], s[4:5], v0, s33, v[2:3]
	s_and_b32 s4, s37, 0x1c0
	v_mad_i32_i24 v3, v1, s33, v3
	s_lshl_b32 s10, s4, 1
	v_lshl_add_u64 v[0:1], v[2:3], 0, s[10:11]
	v_lshlrev_b32_e32 v2, 1, v88
	v_mov_b32_e32 v3, v87
	v_lshl_add_u64 v[0:1], v[0:1], 0, v[2:3]
	s_lshl_b32 s10, s4, 2
	v_lshl_add_u64 v[2:3], v[0:1], 0, s[12:13]
	v_add_co_u32_e32 v0, vcc, s36, v0
	s_add_u32 s4, s48, s10
	s_nop 0
	v_addc_co_u32_e32 v1, vcc, 0, v1, vcc
	s_addc_u32 s5, s49, 0
	global_load_dwordx4 v[16:19], v[0:1], off offset:2048
	global_load_dwordx4 v[20:23], v[2:3], off offset:16
	v_lshlrev_b32_e32 v0, 2, v88
	s_add_u32 s48, s50, s10
	s_addc_u32 s49, s51, 0
	global_load_dwordx4 v[24:27], v0, s[4:5] offset:48
	global_load_dwordx4 v[28:31], v0, s[4:5] offset:32
	global_load_dwordx4 v[32:35], v0, s[4:5] offset:16
	global_load_dwordx4 v[36:39], v0, s[4:5]
	global_load_dwordx4 v[56:59], v0, s[48:49] offset:48
	global_load_dwordx4 v[60:63], v0, s[48:49] offset:32
	global_load_dwordx4 v[64:67], v0, s[48:49] offset:16
	global_load_dwordx4 v[68:71], v0, s[48:49]
